# bundle: v87 plus attention task-prologue load hoisting, XCD-leader early invalidate, modulation GEMV counted wait, S5 x-tile pitch 288 B
# baseline (speedup 1.0000x reference)
; __device__ __forceinline__ unsigned xb_add(unsigned* p, unsigned v) { return __hip_atomic_fetch_add(p, v, __ATOMIC_RELAXED, __HIP_MEMORY_SCOPE_AGENT); }
; __device__ __forceinline__ void xcd_barrier(const XcdBarrier& b) {
;     ...
;         const unsigned old = xb_add(&bar[XB_XSUB(b.x)], 1u);
;         const unsigned gen = old / nloc;
;         if (old + 1u == (gen + 1u) * nloc) {
;             __builtin_amdgcn_fence(__ATOMIC_RELEASE, "agent");
;             asm volatile("s_waitcnt vmcnt(0)" ::: "memory");
;             const unsigned og = xb_add(&bar[XB_TOP], 1u);
;             const unsigned tg = og / nx;
;             if (og + 1u == (tg + 1u) * nx) xb_add(&bar[XB_TOPGEN], 1u);
.LBB0_139:
	s_andn2_saveexec_b64 s[12:13], s[12:13]
	s_cbranch_execz .LBB0_159
	s_mov_b64 s[12:13], exec
	buffer_wbl2 sc1
	buffer_inv sc1
	s_waitcnt lgkmcnt(0)
	s_waitcnt vmcnt(0)
	v_mbcnt_lo_u32_b32 v1, s12, 0
	v_mbcnt_hi_u32_b32 v1, s13, v1
	v_cmp_eq_u32_e32 vcc, 0, v1
	s_and_saveexec_b64 s[14:15], vcc
	s_cbranch_execz .LBB0_142
	s_bcnt1_i32_b64 s3, s[12:13]
	v_mov_b32_e32 v2, 0x83000
	v_mov_b32_e32 v3, s3
	global_atomic_add v2, v2, v3, s[26:27] offset:1024 sc0

; __device__ __forceinline__ unsigned xb_ld(unsigned* p)              { return __hip_atomic_load(p, __ATOMIC_RELAXED, __HIP_MEMORY_SCOPE_AGENT); }
; __device__ __forceinline__ unsigned xb_add(unsigned* p, unsigned v) { return __hip_atomic_fetch_add(p, v, __ATOMIC_RELAXED, __HIP_MEMORY_SCOPE_AGENT); }
; #define XB_SPIN(cond, bar) do { unsigned _sp = 0; while (cond) { __builtin_amdgcn_s_sleep(1); \
;     if ((++_sp & 255u) == 0u) { if (xb_ld(&(bar)[XB_TMO])) break; if (_sp > XB_SPIN_CAP) { atomicAdd(&(bar)[XB_TMO], 1u); break; } } } } while (0)
; __device__ __forceinline__ void xcd_barrier(const XcdBarrier& b) {
;     ...
;             else XB_SPIN(xb_ld(&bar[XB_TOPGEN]) == tg, bar);
;             __builtin_amdgcn_fence(__ATOMIC_ACQUIRE, "agent");
;             xb_add(&bar[XB_XGEN(b.x)], 1u);
;             asm volatile("s_waitcnt vmcnt(0)" ::: "memory");
.LBB0_156:
	s_or_b64 exec, exec, s[12:13]
	s_mov_b64 s[12:13], exec
	v_mbcnt_lo_u32_b32 v0, s12, 0
	v_mbcnt_hi_u32_b32 v0, s13, v0
	v_cmp_eq_u32_e32 vcc, 0, v0
	s_waitcnt vmcnt(0)
	s_and_saveexec_b64 s[14:15], vcc
	s_cbranch_execz .LBB0_158
	s_bcnt1_i32_b64 s3, s[12:13]
	v_mov_b32_e32 v0, 0x2000
	v_mov_b32_e32 v1, s3
	global_atomic_add v0, v1, s[10:11] offset:1024

; __device__ __forceinline__ unsigned xb_add(unsigned* p, unsigned v) { return __hip_atomic_fetch_add(p, v, __ATOMIC_RELAXED, __HIP_MEMORY_SCOPE_AGENT); }
; __device__ __forceinline__ void xcd_barrier(const XcdBarrier& b) {
;     ...
;         const unsigned old = xb_add(&bar[XB_XSUB(b.x)], 1u);
;         const unsigned gen = old / nloc;
;         if (old + 1u == (gen + 1u) * nloc) {
;             __builtin_amdgcn_fence(__ATOMIC_RELEASE, "agent");
;             asm volatile("s_waitcnt vmcnt(0)" ::: "memory");
;             const unsigned og = xb_add(&bar[XB_TOP], 1u);
;             const unsigned tg = og / nx;
;             if (og + 1u == (tg + 1u) * nx) xb_add(&bar[XB_TOPGEN], 1u);
.LBB0_807:
	s_andn2_saveexec_b64 s[10:11], s[10:11]
	s_cbranch_execz .LBB0_827
	s_mov_b64 s[10:11], exec
	buffer_wbl2 sc1
	buffer_inv sc1
	s_waitcnt lgkmcnt(0)
	s_waitcnt vmcnt(0)
	v_mbcnt_lo_u32_b32 v1, s10, 0
	v_mbcnt_hi_u32_b32 v1, s11, v1
	v_cmp_eq_u32_e32 vcc, 0, v1
	s_and_saveexec_b64 s[12:13], vcc
	s_cbranch_execz .LBB0_810
	s_bcnt1_i32_b64 s3, s[10:11]
	v_mov_b32_e32 v2, 0x83000
	v_mov_b32_e32 v3, s3
	global_atomic_add v2, v2, v3, s[26:27] offset:1024 sc0

; __device__ __forceinline__ unsigned xb_ld(unsigned* p)              { return __hip_atomic_load(p, __ATOMIC_RELAXED, __HIP_MEMORY_SCOPE_AGENT); }
; __device__ __forceinline__ unsigned xb_add(unsigned* p, unsigned v) { return __hip_atomic_fetch_add(p, v, __ATOMIC_RELAXED, __HIP_MEMORY_SCOPE_AGENT); }
; #define XB_SPIN(cond, bar) do { unsigned _sp = 0; while (cond) { __builtin_amdgcn_s_sleep(1); \
;     if ((++_sp & 255u) == 0u) { if (xb_ld(&(bar)[XB_TMO])) break; if (_sp > XB_SPIN_CAP) { atomicAdd(&(bar)[XB_TMO], 1u); break; } } } } while (0)
; __device__ __forceinline__ void xcd_barrier(const XcdBarrier& b) {
;     ...
;             else XB_SPIN(xb_ld(&bar[XB_TOPGEN]) == tg, bar);
;             __builtin_amdgcn_fence(__ATOMIC_ACQUIRE, "agent");
;             xb_add(&bar[XB_XGEN(b.x)], 1u);
;             asm volatile("s_waitcnt vmcnt(0)" ::: "memory");
.LBB0_824:
	s_or_b64 exec, exec, s[10:11]
	s_mov_b64 s[10:11], exec
	v_mbcnt_lo_u32_b32 v0, s10, 0
	v_mbcnt_hi_u32_b32 v0, s11, v0
	v_cmp_eq_u32_e32 vcc, 0, v0
	s_waitcnt vmcnt(0)
	s_and_saveexec_b64 s[12:13], vcc
	s_cbranch_execz .LBB0_826
	s_bcnt1_i32_b64 s3, s[10:11]
	v_mov_b32_e32 v0, 0x2000
	v_mov_b32_e32 v1, s3
	global_atomic_add v0, v1, s[8:9] offset:1024

; __device__ __forceinline__ unsigned pk2(float lo, float hi) { unsigned r; asm("v_cvt_pk_bf16_f32 %0, %1, %2" : "=v"(r) : "v"(lo), "v"(hi)); return r; }
; __device__ __forceinline__ void phase_na_attn(const Fr& F) {
;     ...
;         __syncthreads();
;         if (tid < 465) rpbT[tid] = F.a->in[24][h * 465 + tid];
;         bf16x8 Qf[2];
;         {
;             u32x4 qw[2]; float qv[2][8]; float ss = 0.f;
; #pragma unroll
;             for (int ds = 0; ds < 2; ++ds) { qw[ds] = *(const u32x4*)(Qn + (size_t)(qrow0 + l15) * D + h * 64 + 32 * ds + 8 * lq);
; #pragma unroll
;                 for (int i = 0; i < 4; ++i) { qv[ds][2 * i] = lo_bf(qw[ds][i]); qv[ds][2 * i + 1] = hi_bf(qw[ds][i]); ss += qv[ds][2 * i] * qv[ds][2 * i] + qv[ds][2 * i + 1] * qv[ds][2 * i + 1]; } }
;             ss += __shfl_xor(ss, 16); ss += __shfl_xor(ss, 32);
;             const float rstd = 0.125f / sqrtf(ss * (1.f / 64.f) + 1e-6f);
; #pragma unroll
;             for (int ds = 0; ds < 2; ++ds) { const float* qg = F.a->in[22] + 32 * ds + 8 * lq; u32x4 o;
; #pragma unroll
;                 for (int i = 0; i < 4; ++i) o[i] = pk2(qv[ds][2 * i] * rstd * qg[2 * i], qv[ds][2 * i + 1] * rstd * qg[2 * i + 1]);
;                 Qf[ds] = __builtin_bit_cast(bf16x8, o); }
;         }
.LBB0_1067:
	s_and_b32 s12, s12, 15
	s_barrier
	s_and_saveexec_b64 s[8:9], s[6:7]
	s_cbranch_execz .LBB0_1069
	s_mul_i32 s14, s12, 0x1d1
	v_add_lshl_u32 v103, s14, v128, 2
	global_load_dword v103, v103, s[42:43]
.LBB0_1069:
	s_or_b64 exec, exec, s[8:9]
	v_add_u32_e32 v72, s13, v61
	v_ashrrev_i32_e32 v73, 31, v72
	v_lshlrev_b64 v[8:9], 11, v[72:73]
	v_lshl_add_u64 v[8:9], s[46:47], 0, v[8:9]
	s_lshl_b32 s50, s12, 7
	v_lshl_add_u64 v[8:9], v[8:9], 0, s[50:51]
	v_lshl_add_u64 v[12:13], v[8:9], 0, v[70:71]
	global_load_dwordx4 v[8:11], v[12:13], off
	s_nop 0
	global_load_dwordx4 v[12:15], v[12:13], off offset:64
	s_nop 0
	global_load_dwordx4 v[16:19], v[68:69], off
	global_load_dwordx4 v[20:23], v[68:69], off offset:16
	global_load_dwordx4 v[24:27], v[68:69], off offset:128
	global_load_dwordx4 v[28:31], v[68:69], off offset:144
	s_cmp_lt_i32 s79, 1
	s_cbranch_scc0 .LBB0_1071
	s_lshl_b32 s8, s79, 6
	s_sub_i32 s50, 0, s8
	s_lshl_b32 s13, s78, 6
	s_mov_b64 s[8:9], 0

; __device__ __forceinline__ unsigned pk2(float lo, float hi) { unsigned r; asm("v_cvt_pk_bf16_f32 %0, %1, %2" : "=v"(r) : "v"(lo), "v"(hi)); return r; }
; __device__ __forceinline__ void phase_na_attn(const Fr& F) {
;     ...
;         if (tid < 465) rpbT[tid] = F.a->in[24][h * 465 + tid];
;         bf16x8 Qf[2];
;         {
;             u32x4 qw[2]; float qv[2][8]; float ss = 0.f;
; #pragma unroll
;             for (int ds = 0; ds < 2; ++ds) { qw[ds] = *(const u32x4*)(Qn + (size_t)(qrow0 + l15) * D + h * 64 + 32 * ds + 8 * lq);
; #pragma unroll
;                 for (int i = 0; i < 4; ++i) { qv[ds][2 * i] = lo_bf(qw[ds][i]); qv[ds][2 * i + 1] = hi_bf(qw[ds][i]); ss += qv[ds][2 * i] * qv[ds][2 * i] + qv[ds][2 * i + 1] * qv[ds][2 * i + 1]; } }
;             ss += __shfl_xor(ss, 16); ss += __shfl_xor(ss, 32);
;             const float rstd = 0.125f / sqrtf(ss * (1.f / 64.f) + 1e-6f);
; #pragma unroll
;             for (int ds = 0; ds < 2; ++ds) { const float* qg = F.a->in[22] + 32 * ds + 8 * lq; u32x4 o;
; #pragma unroll
;                 for (int i = 0; i < 4; ++i) o[i] = pk2(qv[ds][2 * i] * rstd * qg[2 * i], qv[ds][2 * i + 1] * rstd * qg[2 * i + 1]);
;                 Qf[ds] = __builtin_bit_cast(bf16x8, o); }
;         }
;         f32x4 O[4]; float lsum = 0.f;
; #pragma unroll
;         for (int dt = 0; dt < 4; ++dt) O[dt] = (f32x4){0.f, 0.f, 0.f, 0.f};
;         const bf16* Kg = Kn + (size_t)b * TB * D + h * 64 + spart + (size_t)srow * D;
;         const bf16* Vg = VT + ((size_t)(b * 16 + h) * 64 + srow) * TB + spart;
;         u32x4 kr0, vr0, kr1, vr1;
;     ...
;         { const int t0 = NA_T0(0); kr0 = *(const u32x4*)(Kg + (size_t)t0 * D); vr0 = *(const u32x4*)(Vg + t0); }
;         { const int t1 = NA_T0(1); kr1 = *(const u32x4*)(Kg + (size_t)t1 * D); vr1 = *(const u32x4*)(Vg + t1); }
;         *(u32x4*)(KV + srow * KST + spart) = knorm(kr0); *(u32x4*)(KV + 64 * KST + srow * KST + spart) = vr0;
;         __syncthreads();
.LBB0_1073:
	s_lshl_b32 s80, s12, 6
	s_mul_i32 s9, s11, 0x880000
	s_mul_hi_i32 s8, s11, 0x880000
	s_add_u32 s9, s60, s9
	s_addc_u32 s14, s61, s8
	s_lshl_b32 s8, s80, 1
	s_add_u32 s8, s9, s8
	s_addc_u32 s9, s14, 0
	v_lshl_add_u64 v[112:113], s[8:9], 0, v[56:57]
	v_lshl_add_u64 v[74:75], v[112:113], 0, v[62:63]
	s_lshl_b64 s[8:9], s[50:51], 11
	v_lshl_add_u64 v[112:113], v[74:75], 0, s[8:9]
	global_load_dwordx4 v[32:35], v[112:113], off
	s_lshl_b32 s8, s11, 4
	s_or_b32 s8, s8, s12
	s_ashr_i32 s9, s8, 31
	s_lshl_b64 s[8:9], s[8:9], 6
	v_lshl_add_u64 v[112:113], s[8:9], 0, v[58:59]
	v_mad_u64_u32 v[76:77], s[8:9], v112, s72, v[64:65]
	v_mad_i32_i24 v77, v113, s72, v77
	s_lshl_b32 s9, s79, 6
	v_lshl_add_u64 v[112:113], s[50:51], 1, v[76:77]
	s_add_i32 s50, s79, 4
	s_add_i32 s8, s13, 0x140
	s_sub_i32 s9, 64, s9
	s_cmp_gt_i32 s79, 1
	s_cselect_b32 s8, s8, s9
	s_ashr_i32 s9, s8, 31
	s_lshl_b64 s[12:13], s[8:9], 11
	v_lshl_add_u64 v[114:115], v[74:75], 0, s[12:13]
	global_load_dwordx4 v[36:39], v[112:113], off
	v_lshl_add_u64 v[112:113], s[8:9], 1, v[76:77]
	global_load_dwordx4 v[40:43], v[114:115], off
	global_load_dwordx4 v[44:47], v[112:113], off
	s_and_saveexec_b64 s[8:9], s[6:7]
	s_cbranch_execz .Lattn_rpb_skip
	s_waitcnt vmcnt(10)
	ds_write_b32 v67, v103 offset:49152
.Lattn_rpb_skip:
	s_or_b64 exec, exec, s[8:9]
	s_waitcnt vmcnt(9)
	v_and_b32_e32 v105, 0xffff0000, v8
	v_and_b32_e32 v107, 0xffff0000, v9
	v_lshlrev_b32_e32 v104, 16, v8
	v_lshlrev_b32_e32 v106, 16, v9
	v_lshlrev_b32_e32 v108, 16, v10
	v_and_b32_e32 v109, 0xffff0000, v10
	v_lshlrev_b32_e32 v110, 16, v11
	v_and_b32_e32 v111, 0xffff0000, v11
	s_waitcnt vmcnt(8)
	v_lshlrev_b32_e32 v9, 16, v15
	v_lshlrev_b32_e32 v8, 16, v14
	v_and_b32_e32 v11, 0xffff0000, v15
	v_and_b32_e32 v10, 0xffff0000, v14
	v_mul_f32_e32 v14, v105, v105
	v_mul_f32_e32 v15, v107, v107
	v_mul_f32_e32 v116, v109, v109
	v_fmac_f32_e32 v14, v104, v104
	v_fmac_f32_e32 v15, v106, v106
	v_and_b32_e32 v113, 0xffff0000, v12
	v_mul_f32_e32 v117, v111, v111
	v_fmac_f32_e32 v116, v108, v108
	v_add_f32_e32 v14, v14, v15
	v_lshlrev_b32_e32 v112, 16, v12
	v_and_b32_e32 v115, 0xffff0000, v13
	v_mul_f32_e32 v118, v113, v113
	v_fmac_f32_e32 v117, v110, v110
	v_add_f32_e32 v14, v116, v14
	v_lshlrev_b32_e32 v114, 16, v13
	v_mul_f32_e32 v119, v115, v115
	v_fmac_f32_e32 v118, v112, v112
	v_add_f32_e32 v14, v117, v14
	v_pk_mul_f32 v[12:13], v[10:11], v[10:11]
	v_fmac_f32_e32 v119, v114, v114
	v_add_f32_e32 v14, v118, v14
	v_pk_fma_f32 v[12:13], v[8:9], v[8:9], v[12:13]
	v_add_f32_e32 v14, v119, v14
	v_add_f32_e32 v12, v12, v14
	v_add_f32_e32 v12, v13, v12
	ds_bpermute_b32 v13, v78, v12
	s_waitcnt lgkmcnt(0)
	v_add_f32_e32 v12, v12, v13
	ds_bpermute_b32 v13, v79, v12
	s_waitcnt lgkmcnt(0)
	v_add_f32_e32 v12, v12, v13
	v_fmamk_f32 v12, v12, 0x3c800000, v83
	v_mul_f32_e32 v13, 0x4f800000, v12
	v_cmp_gt_f32_e32 vcc, s70, v12
	s_nop 1
	v_cndmask_b32_e32 v12, v12, v13, vcc
	v_sqrt_f32_e32 v13, v12
	s_nop 0
	v_add_u32_e32 v14, -1, v13
	v_add_u32_e32 v15, 1, v13
	v_fma_f32 v116, -v14, v13, v12
	v_fma_f32 v117, -v15, v13, v12
	v_cmp_ge_f32_e64 s[8:9], 0, v116
	s_nop 1
	v_cndmask_b32_e64 v13, v13, v14, s[8:9]
	v_cmp_lt_f32_e64 s[8:9], 0, v117
	s_nop 1
	v_cndmask_b32_e64 v13, v13, v15, s[8:9]
	v_mul_f32_e32 v14, 0x37800000, v13
	v_cndmask_b32_e32 v13, v13, v14, vcc
	v_cmp_class_f32_e32 vcc, v12, v84
	s_nop 1
	v_cndmask_b32_e32 v12, v13, v12, vcc
	v_div_scale_f32 v13, s[8:9], v12, v12, s71
	v_rcp_f32_e32 v14, v13
	v_div_scale_f32 v15, vcc, s71, v12, s71
	s_mov_b64 s[8:9], -1
	v_fma_f32 v116, -v13, v14, 1.0
	v_fmac_f32_e32 v14, v116, v14
	v_mul_f32_e32 v116, v15, v14
	v_fma_f32 v117, -v13, v116, v15
	v_fmac_f32_e32 v116, v117, v14
	v_fma_f32 v13, -v13, v116, v15
	v_div_fmas_f32 v13, v13, v14, v116
	v_div_fixup_f32 v12, v13, v12, s71
	v_mul_f32_e32 v13, v12, v104
	v_mul_f32_e32 v14, v12, v105
	v_mul_f32_e32 v15, v12, v106
	v_mul_f32_e32 v104, v12, v107
	v_mul_f32_e32 v105, v12, v108
	v_mul_f32_e32 v106, v12, v109
	v_mul_f32_e32 v107, v12, v110
	v_mul_f32_e32 v108, v12, v111
	v_mul_f32_e32 v109, v12, v112
	v_mul_f32_e32 v110, v12, v113
	v_mul_f32_e32 v111, v12, v114
	v_mul_f32_e32 v112, v12, v115
	v_mul_f32_e32 v8, v12, v8
	v_mul_f32_e32 v10, v12, v10
	v_mul_f32_e32 v9, v12, v9
	v_mul_f32_e32 v11, v12, v11
	s_waitcnt vmcnt(7)
	v_mul_f32_e32 v12, v16, v13
	v_mul_f32_e32 v13, v17, v14
	v_mul_f32_e32 v14, v18, v15
	v_mul_f32_e32 v15, v19, v104
	s_waitcnt vmcnt(6)
	v_mul_f32_e32 v16, v20, v105
	v_mul_f32_e32 v17, v21, v106
	v_mul_f32_e32 v18, v22, v107
	v_mul_f32_e32 v19, v23, v108
	s_waitcnt vmcnt(5)
	v_mul_f32_e32 v20, v24, v109
	v_mul_f32_e32 v21, v25, v110
	v_mul_f32_e32 v22, v111, v26
	v_mul_f32_e32 v23, v112, v27
	s_waitcnt vmcnt(4)
	v_mul_f32_e32 v8, v8, v28
	v_mul_f32_e32 v10, v10, v29
	v_mul_f32_e32 v9, v9, v30
	v_mul_f32_e32 v11, v11, v31
	v_cvt_pk_bf16_f32 v28, v12, v13
	v_cvt_pk_bf16_f32 v29, v14, v15
	v_cvt_pk_bf16_f32 v30, v16, v17
	v_cvt_pk_bf16_f32 v31, v18, v19
	v_cvt_pk_bf16_f32 v24, v20, v21
	v_cvt_pk_bf16_f32 v25, v22, v23
	v_cvt_pk_bf16_f32 v26, v8, v10
	v_cvt_pk_bf16_f32 v27, v9, v11
	s_cmp_lt_i32 s79, -2
	s_waitcnt vmcnt(3)
	v_and_b32_e32 v11, 0xffff0000, v34
	v_and_b32_e32 v10, 0xffff0000, v32
	v_and_b32_e32 v15, 0xffff0000, v35
	v_and_b32_e32 v14, 0xffff0000, v33
	v_lshlrev_b32_e32 v9, 16, v34
	v_lshlrev_b32_e32 v8, 16, v32
	v_lshlrev_b32_e32 v13, 16, v35
	v_lshlrev_b32_e32 v12, 16, v33
	v_pk_mul_f32 v[16:17], v[10:11], v[10:11]
	v_pk_mul_f32 v[18:19], v[14:15], v[14:15]
	v_pk_fma_f32 v[16:17], v[8:9], v[8:9], v[16:17]
	v_pk_fma_f32 v[18:19], v[12:13], v[12:13], v[18:19]
	s_waitcnt vmcnt(2)
	ds_write_b128 v80, v[36:39] offset:9216
	v_pk_add_f32 v[16:17], v[16:17], v[18:19]
	s_nop 0
	v_add_f32_e32 v16, v16, v17
	s_nop 1
	v_add_f32_dpp v16, v16, v16 quad_perm:[1,0,3,2] row_mask:0xf bank_mask:0xf bound_ctrl:1
	s_nop 1
	v_add_f32_dpp v16, v16, v16 quad_perm:[2,3,0,1] row_mask:0xf bank_mask:0xf bound_ctrl:1
	s_nop 1
	v_add_f32_dpp v16, v16, v16 row_half_mirror row_mask:0xf bank_mask:0xf bound_ctrl:1
	v_fmamk_f32 v16, v16, 0x3c800000, v83
	v_rsq_f32_e32 v16, v16
	s_nop 0
	v_mul_f32_e32 v8, v16, v8
	v_mul_f32_e32 v10, v16, v10
	v_mul_f32_e32 v11, v16, v11
	v_mul_f32_e32 v12, v16, v12
	v_mul_f32_e32 v14, v16, v14
	v_mul_f32_e32 v9, v16, v9
	v_mul_f32_e32 v13, v16, v13
	v_mul_f32_e32 v15, v16, v15
	v_mul_f32_e32 v8, v0, v8
	v_mul_f32_e32 v10, v1, v10
	v_mul_f32_e32 v11, v5, v11
	v_mul_f32_e32 v12, v2, v12
	v_mul_f32_e32 v14, v3, v14
	v_mul_f32_e32 v16, v4, v9
	v_mul_f32_e32 v13, v6, v13
	v_mul_f32_e32 v15, v7, v15
	v_cvt_pk_bf16_f32 v8, v8, v10
	v_cvt_pk_bf16_f32 v9, v12, v14
	v_cvt_pk_bf16_f32 v10, v16, v11
	v_cvt_pk_bf16_f32 v11, v13, v15
	ds_write_b128 v80, v[8:11]
	s_waitcnt lgkmcnt(0)
	s_barrier
; __device__ __forceinline__ void phase_na_attn(const Fr& F) {
;     ...
;         const int ntl = nrows + 4;
;         int boff[2][4];
; #pragma unroll
;         for (int st = 0; st < 2; ++st)
; #pragma unroll
;             for (int reg = 0; reg < 4; ++reg) { const int c = lo + 16 * st + 4 * lq + reg, qc = q0 + l15, cs = min(max(qc - 8, 0), 48); boff[st][reg] = (c >= cs && c < cs + 16) ? c - qc + 15 : -1; }
;     ...
;         f32x4 O[4]; float lsum = 0.f;
; #pragma unroll
;         for (int dt = 0; dt < 4; ++dt) O[dt] = (f32x4){0.f, 0.f, 0.f, 0.f};
	s_cbranch_scc1 .LBB0_1199
	v_or_b32_e32 v8, s10, v61
	v_max_i32_e32 v9, 8, v8
	v_add_u32_e32 v9, -8, v9
	v_min_u32_e32 v9, 48, v9
	v_add_u32_e32 v10, s75, v60
	v_add_u32_e32 v11, 16, v9
	v_cmp_ge_i32_e32 vcc, v10, v9
	v_cmp_lt_i32_e64 s[8:9], v10, v11
	v_sub_u32_e32 v12, v10, v8
	v_add_u32_e32 v13, 15, v12
	s_and_b64 vcc, vcc, s[8:9]
	v_add_u32_e32 v14, 1, v10
	v_cndmask_b32_e32 v13, -1, v13, vcc
	v_cmp_ge_i32_e32 vcc, v14, v9
	v_cmp_lt_i32_e64 s[8:9], v14, v11
	v_add_u32_e32 v14, 16, v10
	v_sub_u32_e32 v15, v14, v8
	s_and_b64 vcc, vcc, s[8:9]
	v_add_u32_e32 v16, 2, v10
	v_cndmask_b32_e32 v15, -1, v15, vcc
	v_cmp_ge_i32_e32 vcc, v16, v9
	v_cmp_lt_i32_e64 s[8:9], v16, v11
	v_add_u32_e32 v16, 17, v10
	v_sub_u32_e32 v17, v16, v8
	s_and_b64 vcc, vcc, s[8:9]
	v_add_u32_e32 v18, 3, v10
	v_cndmask_b32_e32 v17, -1, v17, vcc
	v_cmp_ge_i32_e32 vcc, v18, v9
	v_cmp_lt_i32_e64 s[8:9], v18, v11
	v_add_u32_e32 v18, 18, v10
	v_sub_u32_e32 v8, v18, v8
	s_and_b64 vcc, vcc, s[8:9]
	v_cndmask_b32_e32 v8, -1, v8, vcc
	v_cmp_ge_i32_e32 vcc, v14, v9
	v_cmp_lt_i32_e64 s[8:9], v10, v9
	v_add_u32_e32 v14, 31, v12
	s_and_b64 vcc, vcc, s[8:9]
	v_cndmask_b32_e32 v14, -1, v14, vcc
	v_cmp_ge_i32_e32 vcc, v16, v9
	v_cmp_lt_i32_e64 s[8:9], v16, v11
	v_add_u32_e32 v16, 32, v12
	s_and_b64 vcc, vcc, s[8:9]
	v_cndmask_b32_e32 v16, -1, v16, vcc
	v_cmp_ge_i32_e32 vcc, v18, v9
	v_cmp_lt_i32_e64 s[8:9], v18, v11
	v_add_u32_e32 v18, 33, v12
	s_and_b64 vcc, vcc, s[8:9]
	v_add_u32_e32 v10, 19, v10
	v_cndmask_b32_e32 v18, -1, v18, vcc
	v_cmp_ge_i32_e32 vcc, v10, v9
	v_cmp_lt_i32_e64 s[8:9], v10, v11
	v_add_u32_e32 v9, 34, v12
	s_and_b64 vcc, vcc, s[8:9]
	v_cndmask_b32_e32 v9, -1, v9, vcc
	v_mov_b32_e32 v10, v57
	v_mov_b32_e32 v11, v57
	v_cmp_lt_i32_e64 s[8:9], -1, v13
	v_cmp_lt_i32_e64 s[10:11], -1, v15
	v_cmp_lt_i32_e64 s[12:13], -1, v17
	v_cmp_lt_i32_e64 s[14:15], -1, v8
	v_cmp_lt_i32_e64 s[16:17], -1, v14
	v_cmp_lt_i32_e64 s[18:19], -1, v16
	v_cmp_lt_i32_e64 s[20:21], -1, v18
	v_cmp_lt_i32_e64 s[22:23], -1, v9
	v_lshl_add_u32 v87, v13, 2, 0
	v_lshl_add_u32 v88, v15, 2, 0
	v_lshl_add_u32 v89, v17, 2, 0
	v_lshl_add_u32 v90, v8, 2, 0
	v_lshl_add_u32 v91, v14, 2, 0
	v_lshl_add_u32 v92, v16, 2, 0
	v_lshl_add_u32 v93, v18, 2, 0
	v_lshl_add_u32 v94, v9, 2, 0
	v_mov_b32_e32 v8, v57
	v_mov_b32_e32 v9, v57
	v_mov_b64_e32 v[14:15], v[10:11]
	v_mov_b64_e32 v[18:19], v[10:11]
	v_mov_b64_e32 v[22:23], v[10:11]
	s_add_i32 s81, s77, 8
	s_mov_b32 s83, 0
	v_mov_b32_e32 v86, 0
	v_mov_b64_e32 v[12:13], v[8:9]
	v_mov_b64_e32 v[16:17], v[8:9]
	v_mov_b64_e32 v[20:21], v[8:9]

; __device__ __forceinline__ unsigned xb_add(unsigned* p, unsigned v) { return __hip_atomic_fetch_add(p, v, __ATOMIC_RELAXED, __HIP_MEMORY_SCOPE_AGENT); }
; __device__ __forceinline__ void xcd_barrier(const XcdBarrier& b) {
;     ...
;         if (old + 1u == (gen + 1u) * nloc) {
;             __builtin_amdgcn_fence(__ATOMIC_RELEASE, "agent");
;             asm volatile("s_waitcnt vmcnt(0)" ::: "memory");
;             const unsigned og = xb_add(&bar[XB_TOP], 1u);
.LBB0_2703:
	s_andn2_saveexec_b64 s[4:5], s[4:5]
	s_cbranch_execz .LBB0_2723
	s_mov_b64 s[4:5], exec
	buffer_wbl2 sc1
	buffer_inv sc1
	s_waitcnt lgkmcnt(0)
	s_waitcnt vmcnt(0)
	v_mbcnt_lo_u32_b32 v1, s4, 0
	v_mbcnt_hi_u32_b32 v1, s5, v1
	v_cmp_eq_u32_e32 vcc, 0, v1
	s_and_saveexec_b64 s[6:7], vcc
	s_cbranch_execz .LBB0_2706
	s_bcnt1_i32_b64 s4, s[4:5]
	v_mov_b32_e32 v2, 0x83000
	v_mov_b32_e32 v3, s4
	global_atomic_add v2, v2, v3, s[26:27] offset:1024 sc0

; __device__ __forceinline__ unsigned xb_ld(unsigned* p)              { return __hip_atomic_load(p, __ATOMIC_RELAXED, __HIP_MEMORY_SCOPE_AGENT); }
; __device__ __forceinline__ unsigned xb_add(unsigned* p, unsigned v) { return __hip_atomic_fetch_add(p, v, __ATOMIC_RELAXED, __HIP_MEMORY_SCOPE_AGENT); }
; #define XB_SPIN(cond, bar) do { unsigned _sp = 0; while (cond) { __builtin_amdgcn_s_sleep(1); \
;     if ((++_sp & 255u) == 0u) { if (xb_ld(&(bar)[XB_TMO])) break; if (_sp > XB_SPIN_CAP) { atomicAdd(&(bar)[XB_TMO], 1u); break; } } } } while (0)
; __device__ __forceinline__ void xcd_barrier(const XcdBarrier& b) {
;     ...
;             else XB_SPIN(xb_ld(&bar[XB_TOPGEN]) == tg, bar);
;             __builtin_amdgcn_fence(__ATOMIC_ACQUIRE, "agent");
;             xb_add(&bar[XB_XGEN(b.x)], 1u);
.LBB0_2720:
	s_or_b64 exec, exec, s[4:5]
	s_mov_b64 s[4:5], exec
	v_mbcnt_lo_u32_b32 v0, s4, 0
	v_mbcnt_hi_u32_b32 v0, s5, v0
	v_cmp_eq_u32_e32 vcc, 0, v0
	s_waitcnt vmcnt(0)
	s_and_saveexec_b64 s[6:7], vcc
	s_cbranch_execz .LBB0_2722
	s_bcnt1_i32_b64 s4, s[4:5]
	v_mov_b32_e32 v0, 0x2000
	v_mov_b32_e32 v1, s4
	global_atomic_add v0, v1, s[2:3] offset:1024
